# context rows owned per XCD (residual ctx tiles remapped; counters per XCD / XCD pair) + XCDs 4..7 start each post-attention chain ~37us later so the two halves' memory-bound phases alternate
# baseline (speedup 1.0000x reference)
; #define GRID_SYNC() do { nbar += (unsigned)gridDim.x; grid_barrier(barw, nbar); } while (0)
; __global__ void __launch_bounds__(512, 2) fwd_megakernel(Args args) {
;     ...
;             if (!(op == 4 || op == 6 || op == 7 || skip0)) GRID_SYNC();
;         }
.Llb_A:
	s_mov_b64 exec, s[4:5]
	s_barrier
	v_readlane_b32 s2, v255, 0
	s_bitcmp1_b32 s2, 2
	s_cbranch_scc0 .Lofs_skip
	s_sleep 127
	s_sleep 127
	s_sleep 127
	s_sleep 127
	s_sleep 127
	s_sleep 127
	s_sleep 127
	s_sleep 127
	s_sleep 127
	s_sleep 127
.Lofs_skip:
	s_branch .LBB0_585
.Lat_not9:
	s_cmp_eq_u32 s44, 2
	s_cbranch_scc0 .Lxl_not2
	s_branch .Lxl_yes
